# K bank-conflict fix + attention tile loop entry placed on a 64-byte boundary (never-executed padding)
# speedup vs baseline: 1.0063x; 1.0002x over previous
.LBB0_338:
	s_or_b64 exec, exec, s[12:13]
	v_mov_b32_e32 v51, s43
	v_mov_b32_e32 v56, s42
	v_cmp_gt_i32_e64 s[12:13], 0, v185
	s_nop 1
	v_max_f32_e32 v57, v18, v18
	v_mov_b32_e32 v190, 0
	v_cndmask_b32_e64 v51, v51, v56, s[12:13]
	v_cndmask_b32_e64 v56, v51, 0, s[8:9]
	v_max_f32_e32 v51, v19, v19
	v_max_f32_e32 v51, v57, v51
	v_max3_f32 v51, v51, v20, v21
	v_max3_f32 v51, v51, v22, v23
	v_max3_f32 v51, v51, v24, v25
	v_max3_f32 v51, v51, v26, v27
	v_max3_f32 v51, v51, v28, v29
	v_max3_f32 v51, v51, v30, v31
	v_max3_f32 v51, v51, v32, v33
	v_max3_f32 v51, v51, v2, v3
	v_max3_f32 v51, v51, v4, v5
	v_max3_f32 v51, v51, v6, v7
	v_max3_f32 v51, v51, v8, v9
	v_max3_f32 v51, v51, v10, v11
	v_max3_f32 v51, v51, v12, v13
	v_max3_f32 v51, v51, v14, v15
	v_max3_f32 v51, v51, v16, v17
	v_mov_b32_e32 v57, v51
	s_nop 1
	v_permlane32_swap_b32_e32 v51, v57
	v_max_f32_e32 v57, v57, v57
	v_max_f32_e32 v51, v51, v51
	v_max_f32_e32 v51, v51, v57
	v_add_f32_e32 v57, v56, v51
	v_sub_f32_e32 v191, s43, v57
	v_sub_f32_e32 v190, 0, v57
	v_sub_f32_e32 v192, s42, v57
	v_mov_b32_e32 v176, 0
	v_readfirstlane_b32 s98, v185
	s_mov_b32 s99, 64
	v_sub_f32_e32 v56, v56, v57
	v_add_f32_e32 v3, v3, v56
	v_add_f32_e32 v2, v2, v56
	v_add_f32_e32 v4, v4, v56
	v_exp_f32_e32 v196, v3
	v_lshlrev_b32_e32 v3, 4, v55
	s_xor_b64 s[42:43], s[2:3], -1
	v_exp_f32_e32 v195, v2
	v_exp_f32_e32 v197, v4
	v_lshlrev_b32_e32 v2, 3, v55
	v_and_b32_e32 v3, 0xc0, v3
	v_lshlrev_b32_e32 v4, 1, v55
	v_and_or_b32 v3, v2, 24, v3
	v_and_b32_e32 v4, 32, v4
	v_and_b32_e32 v2, 0x100, v2
	s_cmp_lg_u32 0, -1
	v_or3_b32 v2, v3, v4, v2
	s_cselect_b32 s2, 0, 0
	v_add_u32_e32 v180, s2, v2
	s_addk_i32 s2, 0x4000
	v_add_u32_e32 v177, s2, v2
	v_add_lshl_u32 v2, v185, v53, 2
	v_ashrrev_i32_e32 v51, 31, v50
	v_add_f32_e32 v18, v18, v56
	v_add_f32_e32 v19, v19, v56
	v_add_f32_e32 v20, v20, v56
	v_add_f32_e32 v21, v21, v56
	v_add_f32_e32 v22, v22, v56
	v_add_f32_e32 v23, v23, v56
	v_add_f32_e32 v24, v24, v56
	v_add_f32_e32 v25, v25, v56
	v_add_f32_e32 v26, v26, v56
	v_add_f32_e32 v27, v27, v56
	v_add_f32_e32 v28, v28, v56
	v_add_f32_e32 v29, v29, v56
	v_add_f32_e32 v30, v30, v56
	v_add_f32_e32 v31, v31, v56
	v_add_f32_e32 v32, v32, v56
	v_add_f32_e32 v33, v33, v56
	v_add_f32_e32 v5, v5, v56
	v_add_f32_e32 v6, v6, v56
	v_add_f32_e32 v7, v7, v56
	v_add_f32_e32 v8, v8, v56
	v_add_f32_e32 v9, v9, v56
	v_add_f32_e32 v10, v10, v56
	v_add_f32_e32 v11, v11, v56
	v_add_f32_e32 v12, v12, v56
	v_add_f32_e32 v13, v13, v56
	v_add_f32_e32 v14, v14, v56
	v_add_f32_e32 v15, v15, v56
	v_add_f32_e32 v16, v16, v56
	v_add_f32_e32 v17, v17, v56
	v_sub_u32_e32 v2, v98, v2
	s_add_i32 s2, 0, 0x10c80
	v_exp_f32_e32 v199, v18
	v_exp_f32_e32 v201, v19
	v_exp_f32_e32 v202, v20
	v_exp_f32_e32 v205, v21
	v_exp_f32_e32 v207, v22
	v_exp_f32_e32 v209, v23
	v_exp_f32_e32 v211, v24
	v_exp_f32_e32 v213, v25
	v_exp_f32_e32 v215, v26
	v_exp_f32_e32 v216, v27
	v_exp_f32_e32 v217, v28
	v_exp_f32_e32 v218, v29
	v_exp_f32_e32 v221, v30
	v_exp_f32_e32 v222, v31
	v_exp_f32_e32 v223, v32
	v_exp_f32_e32 v224, v33
	v_exp_f32_e32 v198, v5
	v_exp_f32_e32 v200, v6
	v_exp_f32_e32 v203, v7
	v_exp_f32_e32 v204, v8
	v_exp_f32_e32 v206, v9
	v_exp_f32_e32 v208, v10
	v_exp_f32_e32 v210, v11
	v_exp_f32_e32 v212, v12
	v_exp_f32_e32 v214, v13
	v_exp_f32_e32 v150, v14
	v_exp_f32_e32 v151, v15
	v_exp_f32_e32 v152, v16
	v_exp_f32_e32 v153, v17
	v_add_u32_e32 v194, s2, v2
	v_lshl_add_u64 v[2:3], s[30:31], 0, v[50:51]
	s_waitcnt vmcnt(0)
	v_mad_u64_u32 v[4:5], s[2:3], v2, s49, 0
	v_and_b32_e32 v2, 15, v52
	v_mad_i32_i24 v3, v3, s49, v5
	v_lshl_or_b32 v2, v2, 4, v4
	s_mov_b32 s82, 0
	s_waitcnt vmcnt(3)
	ds_write_b128 v183, v[34:37] offset:16384
	s_waitcnt vmcnt(2)
	ds_write_b128 v184, v[38:41] offset:16384
	s_waitcnt vmcnt(0)
	s_mov_b64 s[100:101], exec
	s_and_b64 exec, exec, s[96:97]
	ds_write_b128 v181, v[42:45] offset:49152
	ds_write_b128 v182, v[46:49] offset:49152
	s_mov_b64 exec, s[100:101]
	v_mov_b32_e32 v181, v180
	s_mov_b32 s54, 0
	s_movk_i32 s55, 0x4000
	s_mov_b32 s56, 0x12000
	v_sub_u32_e32 v193, s81, v54
	s_mov_b32 s83, 2
	v_lshl_add_u64 v[160:161], s[40:41], 0, v[2:3]
	s_and_b32 s100, s42, 0x80
	v_lshrrev_b32_e32 v2, 3, v52
	v_sub_u32_e32 v3, v2, v50
	v_mul_u32_u24_e32 v3, 0x2800, v3
	v_and_b32_e32 v4, 8, v52
	v_lshlrev_b32_e32 v4, 4, v4
	v_sub_u32_e32 v3, v3, v4
	v_add_u32_e32 v3, s100, v3
	v_readfirstlane_b32 s101, v50
	v_readfirstlane_b32 s12, v160
	v_readfirstlane_b32 s13, v161
	s_nop 1
	v_subrev_u32_e32 v4, s101, v50
	v_mul_u32_u24_e32 v4, 0x2800, v4
	v_and_b32_e32 v160, 15, v52
	v_lshl_add_u32 v160, v160, 4, v4
	v_add_u32_e32 v161, 0x50000, v160
	v_add_u32_e32 v252, v160, v3
	v_and_b32_e32 v3, 7, v52
	v_and_b32_e32 v4, 7, v2
	v_xor_b32_e32 v3, v3, v4
	v_lshlrev_b32_e32 v3, 4, v3
	v_lshl_or_b32 v235, v2, 8, v3
	v_and_b32_e32 v4, 8, v2
	v_lshl_or_b32 v235, v4, 4, v235
	v_mov_b32_e32 v2, 0
	v_mov_b32_e32 v3, v176
	v_mov_b32_e32 v4, v176
	v_mov_b32_e32 v5, v176
	v_mov_b32_e32 v6, v176
	v_mov_b32_e32 v7, v176
	v_mov_b32_e32 v8, v176
	v_mov_b32_e32 v9, v176
	v_mov_b32_e32 v10, v176
	v_mov_b32_e32 v11, v176
	v_mov_b32_e32 v12, v176
	v_mov_b32_e32 v13, v176
	v_mov_b32_e32 v14, v176
	v_mov_b32_e32 v15, v176
	v_mov_b32_e32 v16, v176
	v_mov_b32_e32 v17, v176
	v_mov_b32_e32 v18, 0
	v_mov_b32_e32 v19, v176
	v_mov_b32_e32 v20, v176
	v_mov_b32_e32 v21, v176
	v_mov_b32_e32 v22, v176
	v_mov_b32_e32 v23, v176
	v_mov_b32_e32 v24, v176
	v_mov_b32_e32 v25, v176
	v_mov_b32_e32 v26, v176
	v_mov_b32_e32 v27, v176
	v_mov_b32_e32 v28, v176
	v_mov_b32_e32 v29, v176
	v_mov_b32_e32 v30, v176
	v_mov_b32_e32 v31, v176
	v_mov_b32_e32 v32, v176
	v_mov_b32_e32 v33, v176
	v_mov_b32_e32 v34, 0
	v_mov_b32_e32 v35, v176
	v_mov_b32_e32 v36, v176
	v_mov_b32_e32 v37, v176
	v_mov_b32_e32 v38, v176
	v_mov_b32_e32 v39, v176
	v_mov_b32_e32 v40, v176
	v_mov_b32_e32 v41, v176
	v_mov_b32_e32 v42, v176
	v_mov_b32_e32 v43, v176
	v_mov_b32_e32 v44, v176
	v_mov_b32_e32 v45, v176
	v_mov_b32_e32 v46, v176
	v_mov_b32_e32 v47, v176
	v_mov_b32_e32 v48, v176
	v_mov_b32_e32 v49, v176
	v_mov_b32_e32 v50, 0
	v_mov_b32_e32 v51, v176
	v_mov_b32_e32 v52, v176
	v_mov_b32_e32 v53, v176
	v_mov_b32_e32 v54, v176
	v_mov_b32_e32 v55, v176
	v_mov_b32_e32 v56, v176
	v_mov_b32_e32 v57, v176
	v_mov_b32_e32 v58, v176
	v_mov_b32_e32 v59, v176
	v_mov_b32_e32 v60, v176
	v_mov_b32_e32 v61, v176
	v_mov_b32_e32 v62, v176
	v_mov_b32_e32 v63, v176
	v_mov_b32_e32 v64, v176
	v_mov_b32_e32 v65, v176
	s_waitcnt lgkmcnt(0)
	s_barrier
	s_branch .LBB0_346
	s_nop 0
	s_nop 0
	s_nop 0
	s_nop 0
	s_nop 0
	s_nop 0
